# adds: group B reads the first V-fragment batch of P.V(t-1) at the end of step t-1 into spare VGPRs (across the barrier); P.V at step top starts without an LDS round trip; no lgkmcnt(0) before the step
# speedup vs baseline: 1.0088x; 1.0088x over previous
.Lkvdma_skip:
	s_mov_b32 s70, s36
	s_cmp_eq_u32 s57, 2
	s_cselect_b64 s[42:43], -1, 0
	s_xor_b64 s[74:75], s[80:81], -1
	s_or_b64 s[42:43], s[74:75], s[42:43]
	s_and_b64 vcc, exec, s[42:43]
	s_cbranch_vccnz .LBB0_148
	s_setprio 1
	v_lshl_add_u32 v210, s37, 14, v218
	s_waitcnt lgkmcnt(0)
	s_nop 0
	v_mfma_f32_32x32x16_bf16 v[32:47], v[76:79], v[154:157], v[32:47]
	ds_read_b64_tr_b16 v[80:81], v210 offset:0x200
	ds_read_b64_tr_b16 v[82:83], v210 offset:0xa00
	v_mfma_f32_32x32x16_bf16 v[32:47], v[72:75], v[158:161], v[32:47]
	ds_read_b64_tr_b16 v[84:85], v210 offset:0x1200
	ds_read_b64_tr_b16 v[86:87], v210 offset:0x1a00
	v_mfma_f32_32x32x16_bf16 v[32:47], v[68:71], v[162:165], v[32:47]
	ds_read_b64_tr_b16 v[88:89], v210 offset:0x2200
	ds_read_b64_tr_b16 v[90:91], v210 offset:0x2a00
	v_mfma_f32_32x32x16_bf16 v[32:47], v[64:67], v[206:209], v[32:47]
	ds_read_b64_tr_b16 v[92:93], v210 offset:0x3200
	ds_read_b64_tr_b16 v[94:95], v210 offset:0x3a00
	s_waitcnt lgkmcnt(0)
	v_mfma_f32_32x32x16_bf16 v[48:63], v[76:79], v[80:83], v[48:63]
	ds_read_b64_tr_b16 v[80:81], v210 offset:0x400
	ds_read_b64_tr_b16 v[82:83], v210 offset:0xc00
	v_mfma_f32_32x32x16_bf16 v[48:63], v[72:75], v[84:87], v[48:63]
	ds_read_b64_tr_b16 v[84:85], v210 offset:0x1400
	ds_read_b64_tr_b16 v[86:87], v210 offset:0x1c00
	v_mfma_f32_32x32x16_bf16 v[48:63], v[68:71], v[88:91], v[48:63]
	ds_read_b64_tr_b16 v[88:89], v210 offset:0x2400
	ds_read_b64_tr_b16 v[90:91], v210 offset:0x2c00
	v_mfma_f32_32x32x16_bf16 v[48:63], v[64:67], v[92:95], v[48:63]
	ds_read_b64_tr_b16 v[92:93], v210 offset:0x3400
	ds_read_b64_tr_b16 v[94:95], v210 offset:0x3c00
	s_waitcnt lgkmcnt(0)
	v_mfma_f32_32x32x16_bf16 v[16:31], v[76:79], v[80:83], v[16:31]
	ds_read_b64_tr_b16 v[80:81], v210 offset:0x600
	ds_read_b64_tr_b16 v[82:83], v210 offset:0xe00
	v_mfma_f32_32x32x16_bf16 v[16:31], v[72:75], v[84:87], v[16:31]
	ds_read_b64_tr_b16 v[84:85], v210 offset:0x1600
	ds_read_b64_tr_b16 v[86:87], v210 offset:0x1e00
	v_mfma_f32_32x32x16_bf16 v[16:31], v[68:71], v[88:91], v[16:31]
	ds_read_b64_tr_b16 v[88:89], v210 offset:0x2600
	ds_read_b64_tr_b16 v[90:91], v210 offset:0x2e00
	v_mfma_f32_32x32x16_bf16 v[16:31], v[64:67], v[92:95], v[16:31]
	ds_read_b64_tr_b16 v[92:93], v210 offset:0x3600
	ds_read_b64_tr_b16 v[94:95], v210 offset:0x3e00
	s_waitcnt lgkmcnt(0)
	v_mfma_f32_32x32x16_bf16 v[0:15], v[76:79], v[80:83], v[0:15]
	v_mfma_f32_32x32x16_bf16 v[0:15], v[72:75], v[84:87], v[0:15]
	v_mfma_f32_32x32x16_bf16 v[0:15], v[68:71], v[88:91], v[0:15]
	v_mfma_f32_32x32x16_bf16 v[0:15], v[64:67], v[92:95], v[0:15]
	s_setprio 0
